# removed duplicate s_waitcnt lgkmcnt(0) after each LDS-read asm block in the GEMM main loop (6 sites)
# baseline (speedup 1.0000x reference)
; #define PG8_STAGE(bufoff, gbase, voff) do { _Pragma("unroll") for (int _i = 0; _i < 2; ++_i) \
;         __builtin_amdgcn_global_load_lds((const unsigned*)((const char*)(gbase) + (voff)[_i]), (LAS unsigned*)(lds + (bufoff) + ldsw + _i * 8192), 16, 0, 0); } while (0)
; #define PG8_LDA(dst, b, h) do { _Pragma("unroll") for (int m = 0; m < 4; ++m) _Pragma("unroll") for (int k = 0; k < 2; ++k) dst[m][k] = *(const LAS bf16x8*)(lds + PG8_SA(b, h) + aoff + m * 2048 + k * 1024); } while (0)
; #define PG8_LDB(dst, b, h) do { _Pragma("unroll") for (int n = 0; n < 2; ++n) _Pragma("unroll") for (int k = 0; k < 2; ++k) dst[n][k] = *(const LAS bf16x8*)(lds + PG8_SB(b, h) + boff + n * 2048 + k * 1024); } while (0)
; #define PG8_MMA(ai, bj, At, Bt) do { __builtin_amdgcn_s_setprio(1); _Pragma("unroll") for (int m = 0; m < 4; ++m) _Pragma("unroll") for (int n = 0; n < 2; ++n) _Pragma("unroll") for (int k = 0; k < 2; ++k) \
;         acc[ai][bj][m][n] = __builtin_amdgcn_mfma_f32_16x16x32_bf16(Bt[n][k], At[m][k], acc[ai][bj][m][n], 0, 0, 0); __builtin_amdgcn_s_setprio(0); } while (0)
; #define PG8_WAIT_V(n) asm volatile("s_waitcnt vmcnt(" #n ")" ::: "memory")
; #define PG8_WAIT_L(n) asm volatile("s_waitcnt lgkmcnt(" #n ")" ::: "memory")
; #define PG8_BAR __builtin_amdgcn_s_barrier()
; #define PG8_SCHED __builtin_amdgcn_sched_barrier(0)
; template <class Epi>
; __device__ __forceinline__ void gemm_phase(LAS unsigned char* lds, const Gemm g, const StaticOrder& S, const Epi& E) {
;     ...
;             PG8_LDB(B0, 0, 0); PG8_SCHED; PG8_LDA(At, 0, 0); PG8_STAGE(PG8_SA(1, 1), a1 + hstepA, voffA);
;             PG8_WAIT_L(8); PG8_BAR; PG8_WAIT_L(0); PG8_MMA(0, 0, At, B0); PG8_BAR; PG8_SCHED;
;             PG8_LDB(B1, 0, 1); PG8_STAGE(PG8_SB(0, 0), b2, voffB);
;             PG8_BAR; PG8_WAIT_L(0); PG8_MMA(0, 1, At, B1); PG8_BAR;
;             PG8_LDA(At, 0, 1); PG8_STAGE(PG8_SA(0, 0), a2, voffA);
;             PG8_BAR; PG8_WAIT_L(0); PG8_MMA(1, 0, At, B0); PG8_BAR; PG8_SCHED;
;             PG8_STAGE(PG8_SB(0, 1), b2 + hstepB, voffB);
;             PG8_WAIT_V(6); PG8_BAR; PG8_MMA(1, 1, At, B1); PG8_BAR;
.LBB0_116:
	s_add_i32 s35, s44, 2
	s_add_u32 s46, s36, 0x80
	s_addc_u32 s45, s37, 0
	s_cmp_eq_u32 s17, s44
	s_cselect_b32 s45, s29, s45
	s_cselect_b32 s44, s28, s46
	s_cselect_b32 s47, s31, s70
	s_cselect_b32 s46, s30, s69
	s_add_i32 s71, 0, 0x10000
	v_lshl_add_u64 v[166:167], s[36:37], 0, v[186:187]
	s_add_i32 m0, s39, 0xc000
	ds_read_b128 v[146:149], v228
	ds_read_b128 v[150:153], v228 offset:1024
	ds_read_b128 v[154:157], v228 offset:2048
	ds_read_b128 v[158:161], v228 offset:3072
	ds_read_b128 v[162:165], v228 offset:4096
	ds_read_b128 v[190:193], v228 offset:5120
	ds_read_b128 v[194:197], v228 offset:6144
	ds_read_b128 v[198:201], v228 offset:7168
	global_load_lds_dwordx4 v[166:167], off
	v_lshl_add_u64 v[166:167], s[36:37], 0, v[188:189]
	s_add_i32 m0, s39, 0xe000
	s_nop 0
	global_load_lds_dwordx4 v[166:167], off
	s_waitcnt lgkmcnt(8)
	s_barrier
	s_waitcnt lgkmcnt(0)
	v_mfma_f32_16x16x32_bf16 v[124:127], v[130:133], v[146:149], v[124:127]
	v_mfma_f32_16x16x32_bf16 v[120:123], v[138:141], v[146:149], v[120:123]
	v_mfma_f32_16x16x32_bf16 v[112:115], v[130:133], v[154:157], v[112:115]
	v_mfma_f32_16x16x32_bf16 v[104:107], v[138:141], v[154:157], v[104:107]
	v_mfma_f32_16x16x32_bf16 v[96:99], v[130:133], v[162:165], v[96:99]
	v_mfma_f32_16x16x32_bf16 v[88:91], v[138:141], v[162:165], v[88:91]
	v_mfma_f32_16x16x32_bf16 v[80:83], v[130:133], v[194:197], v[80:83]
	v_mfma_f32_16x16x32_bf16 v[72:75], v[138:141], v[194:197], v[72:75]
	v_mfma_f32_16x16x32_bf16 v[124:127], v[134:137], v[150:153], v[124:127]
	v_mfma_f32_16x16x32_bf16 v[120:123], v[142:145], v[150:153], v[120:123]
	v_mfma_f32_16x16x32_bf16 v[112:115], v[134:137], v[158:161], v[112:115]
	v_mfma_f32_16x16x32_bf16 v[104:107], v[142:145], v[158:161], v[104:107]
	v_mfma_f32_16x16x32_bf16 v[96:99], v[134:137], v[190:193], v[96:99]
	v_mfma_f32_16x16x32_bf16 v[88:91], v[142:145], v[190:193], v[88:91]
	v_mfma_f32_16x16x32_bf16 v[80:83], v[134:137], v[198:201], v[80:83]
	v_mfma_f32_16x16x32_bf16 v[72:75], v[142:145], v[198:201], v[72:75]
	s_barrier
	s_add_i32 s72, 0, 0x14000
	v_add_u32_e32 v166, s72, v225
	s_add_i32 s71, s71, s57
	ds_read_b128 v[202:205], v166
	ds_read_b128 v[230:233], v166 offset:1024
	ds_read_b128 v[234:237], v166 offset:2048
	ds_read_b128 v[238:241], v166 offset:3072
	v_lshl_add_u64 v[166:167], s[46:47], 0, v[168:169]
	s_mov_b32 m0, s71
	v_lshl_add_u64 v[206:207], s[46:47], 0, v[178:179]
	global_load_lds_dwordx4 v[166:167], off
	s_add_i32 m0, s71, 0x2000
	s_nop 0
	global_load_lds_dwordx4 v[206:207], off
	s_barrier
	s_waitcnt lgkmcnt(0)
	v_mfma_f32_16x16x32_bf16 v[116:119], v[202:205], v[146:149], v[116:119]
	v_mfma_f32_16x16x32_bf16 v[108:111], v[234:237], v[146:149], v[108:111]
	v_mfma_f32_16x16x32_bf16 v[100:103], v[202:205], v[154:157], v[100:103]
	v_mfma_f32_16x16x32_bf16 v[92:95], v[234:237], v[154:157], v[92:95]
	s_mov_b32 m0, s39
	v_lshl_add_u64 v[242:243], s[44:45], 0, v[174:175]
	v_mfma_f32_16x16x32_bf16 v[84:87], v[202:205], v[162:165], v[84:87]
	v_mfma_f32_16x16x32_bf16 v[76:79], v[234:237], v[162:165], v[76:79]
	v_mfma_f32_16x16x32_bf16 v[68:71], v[202:205], v[194:197], v[68:71]
	v_mfma_f32_16x16x32_bf16 v[64:67], v[234:237], v[194:197], v[64:67]
	v_mfma_f32_16x16x32_bf16 v[116:119], v[230:233], v[150:153], v[116:119]
	v_mfma_f32_16x16x32_bf16 v[108:111], v[238:241], v[150:153], v[108:111]
	v_mfma_f32_16x16x32_bf16 v[100:103], v[230:233], v[158:161], v[100:103]
	v_mfma_f32_16x16x32_bf16 v[92:95], v[238:241], v[158:161], v[92:95]
	v_mfma_f32_16x16x32_bf16 v[84:87], v[230:233], v[190:193], v[84:87]
	v_mfma_f32_16x16x32_bf16 v[76:79], v[238:241], v[190:193], v[76:79]
	v_mfma_f32_16x16x32_bf16 v[68:71], v[230:233], v[198:201], v[68:71]
	v_mfma_f32_16x16x32_bf16 v[64:67], v[238:241], v[198:201], v[64:67]
	s_barrier
	ds_read_b128 v[146:149], v228 offset:16384
	ds_read_b128 v[150:153], v228 offset:17408
	ds_read_b128 v[154:157], v228 offset:18432
	ds_read_b128 v[158:161], v228 offset:19456
	ds_read_b128 v[162:165], v228 offset:20480
	ds_read_b128 v[190:193], v228 offset:21504
	ds_read_b128 v[194:197], v228 offset:22528
	ds_read_b128 v[198:201], v228 offset:23552
	global_load_lds_dwordx4 v[242:243], off
	v_lshl_add_u64 v[244:245], s[44:45], 0, v[176:177]
	s_mov_b32 m0, s54
	s_nop 0
	global_load_lds_dwordx4 v[244:245], off
	s_waitcnt vmcnt(10)
	s_barrier
	s_waitcnt lgkmcnt(0)
	v_mfma_f32_16x16x32_bf16 v[60:63], v[130:133], v[146:149], v[60:63]
	v_mfma_f32_16x16x32_bf16 v[56:59], v[138:141], v[146:149], v[56:59]
	v_mfma_f32_16x16x32_bf16 v[52:55], v[130:133], v[154:157], v[52:55]
	v_mfma_f32_16x16x32_bf16 v[44:47], v[138:141], v[154:157], v[44:47]
	v_mfma_f32_16x16x32_bf16 v[36:39], v[130:133], v[162:165], v[36:39]
	v_mfma_f32_16x16x32_bf16 v[28:31], v[138:141], v[162:165], v[28:31]
	v_mfma_f32_16x16x32_bf16 v[20:23], v[130:133], v[194:197], v[20:23]
	v_mfma_f32_16x16x32_bf16 v[12:15], v[138:141], v[194:197], v[12:15]
	v_mfma_f32_16x16x32_bf16 v[60:63], v[134:137], v[150:153], v[60:63]
	v_mfma_f32_16x16x32_bf16 v[56:59], v[142:145], v[150:153], v[56:59]
	v_mfma_f32_16x16x32_bf16 v[52:55], v[134:137], v[158:161], v[52:55]
	v_mfma_f32_16x16x32_bf16 v[44:47], v[142:145], v[158:161], v[44:47]
	v_mfma_f32_16x16x32_bf16 v[36:39], v[134:137], v[190:193], v[36:39]
	v_mfma_f32_16x16x32_bf16 v[28:31], v[142:145], v[190:193], v[28:31]
	v_mfma_f32_16x16x32_bf16 v[20:23], v[134:137], v[198:201], v[20:23]
	v_mfma_f32_16x16x32_bf16 v[12:15], v[142:145], v[198:201], v[12:15]
	s_barrier
; #define PG8_STAGE(bufoff, gbase, voff) do { _Pragma("unroll") for (int _i = 0; _i < 2; ++_i) \
;         __builtin_amdgcn_global_load_lds((const unsigned*)((const char*)(gbase) + (voff)[_i]), (LAS unsigned*)(lds + (bufoff) + ldsw + _i * 8192), 16, 0, 0); } while (0)
; #define PG8_LDA(dst, b, h) do { _Pragma("unroll") for (int m = 0; m < 4; ++m) _Pragma("unroll") for (int k = 0; k < 2; ++k) dst[m][k] = *(const LAS bf16x8*)(lds + PG8_SA(b, h) + aoff + m * 2048 + k * 1024); } while (0)
; #define PG8_LDB(dst, b, h) do { _Pragma("unroll") for (int n = 0; n < 2; ++n) _Pragma("unroll") for (int k = 0; k < 2; ++k) dst[n][k] = *(const LAS bf16x8*)(lds + PG8_SB(b, h) + boff + n * 2048 + k * 1024); } while (0)
; #define PG8_MMA(ai, bj, At, Bt) do { __builtin_amdgcn_s_setprio(1); _Pragma("unroll") for (int m = 0; m < 4; ++m) _Pragma("unroll") for (int n = 0; n < 2; ++n) _Pragma("unroll") for (int k = 0; k < 2; ++k) \
;         acc[ai][bj][m][n] = __builtin_amdgcn_mfma_f32_16x16x32_bf16(Bt[n][k], At[m][k], acc[ai][bj][m][n], 0, 0, 0); __builtin_amdgcn_s_setprio(0); } while (0)
; #define PG8_WAIT_V(n) asm volatile("s_waitcnt vmcnt(" #n ")" ::: "memory")
; #define PG8_WAIT_L(n) asm volatile("s_waitcnt lgkmcnt(" #n ")" ::: "memory")
; #define PG8_BAR __builtin_amdgcn_s_barrier()
; #define PG8_SCHED __builtin_amdgcn_sched_barrier(0)
; template <class Epi>
; __device__ __forceinline__ void gemm_phase(LAS unsigned char* lds, const Gemm g, const StaticOrder& S, const Epi& E) {
;     ...
;             PG8_STAGE(PG8_SB(0, 1), b2 + hstepB, voffB);
;             PG8_WAIT_V(6); PG8_BAR; PG8_MMA(1, 1, At, B1); PG8_BAR;
;             PG8_LDB(B0, 1, 0); PG8_SCHED; PG8_LDA(At, 1, 0); PG8_STAGE(PG8_SA(0, 1), a2 + hstepA, voffA);
;             PG8_WAIT_L(8); PG8_BAR; PG8_WAIT_L(0); PG8_MMA(0, 0, At, B0); PG8_BAR; PG8_SCHED;
;             PG8_LDB(B1, 1, 1); PG8_STAGE(PG8_SB(1, 0), b3, voffB);
	s_add_u32 s46, s46, s50
	s_addc_u32 s47, s47, 0
	s_add_i32 s71, s72, s57
	v_lshl_add_u64 v[246:247], s[46:47], 0, v[168:169]
	s_mov_b32 m0, s71
	v_lshl_add_u64 v[248:249], s[46:47], 0, v[178:179]
	global_load_lds_dwordx4 v[246:247], off
	s_add_i32 m0, s71, 0x2000
	s_nop 0
	global_load_lds_dwordx4 v[248:249], off
	v_add_u32_e32 v142, 0x18000, v225
	ds_read_b128 v[130:133], v142
	ds_read_b128 v[134:137], v142 offset:1024
	ds_read_b128 v[138:141], v142 offset:2048
	ds_read_b128 v[142:145], v142 offset:3072
	s_waitcnt vmcnt(6)
	s_barrier
	v_mfma_f32_16x16x32_bf16 v[48:51], v[202:205], v[146:149], v[48:51]
	v_mfma_f32_16x16x32_bf16 v[40:43], v[234:237], v[146:149], v[40:43]
	v_mfma_f32_16x16x32_bf16 v[32:35], v[202:205], v[154:157], v[32:35]
	v_mfma_f32_16x16x32_bf16 v[24:27], v[234:237], v[154:157], v[24:27]
	s_add_i32 s46, 0, 0x18000
	v_mfma_f32_16x16x32_bf16 v[16:19], v[202:205], v[162:165], v[16:19]
	v_mfma_f32_16x16x32_bf16 v[8:11], v[234:237], v[162:165], v[8:11]
	v_mfma_f32_16x16x32_bf16 v[4:7], v[202:205], v[194:197], v[4:7]
	v_mfma_f32_16x16x32_bf16 v[0:3], v[234:237], v[194:197], v[0:3]
	v_mfma_f32_16x16x32_bf16 v[48:51], v[230:233], v[150:153], v[48:51]
	v_mfma_f32_16x16x32_bf16 v[40:43], v[238:241], v[150:153], v[40:43]
	v_mfma_f32_16x16x32_bf16 v[32:35], v[230:233], v[158:161], v[32:35]
	v_mfma_f32_16x16x32_bf16 v[24:27], v[238:241], v[158:161], v[24:27]
	v_mfma_f32_16x16x32_bf16 v[16:19], v[230:233], v[190:193], v[16:19]
	v_mfma_f32_16x16x32_bf16 v[8:11], v[238:241], v[190:193], v[8:11]
	v_mfma_f32_16x16x32_bf16 v[4:7], v[230:233], v[198:201], v[4:7]
	v_mfma_f32_16x16x32_bf16 v[0:3], v[238:241], v[198:201], v[0:3]
	s_barrier
	s_add_u32 s44, s44, s74
	s_addc_u32 s45, s45, 0
	s_mov_b32 m0, s55
	v_lshl_add_u64 v[202:203], s[44:45], 0, v[174:175]
	ds_read_b128 v[146:149], v228 offset:32768
	ds_read_b128 v[150:153], v228 offset:33792
	ds_read_b128 v[154:157], v228 offset:34816
	ds_read_b128 v[158:161], v228 offset:35840
	ds_read_b128 v[162:165], v228 offset:36864
	ds_read_b128 v[190:193], v228 offset:37888
	ds_read_b128 v[194:197], v228 offset:38912
	ds_read_b128 v[198:201], v228 offset:39936
	global_load_lds_dwordx4 v[202:203], off
	v_lshl_add_u64 v[202:203], s[44:45], 0, v[176:177]
	s_mov_b32 m0, s3
	s_nop 0
	global_load_lds_dwordx4 v[202:203], off
	s_waitcnt lgkmcnt(8)
	s_barrier
	s_waitcnt lgkmcnt(0)
	v_mfma_f32_16x16x32_bf16 v[124:127], v[130:133], v[146:149], v[124:127]
	v_mfma_f32_16x16x32_bf16 v[120:123], v[138:141], v[146:149], v[120:123]
	v_mfma_f32_16x16x32_bf16 v[112:115], v[130:133], v[154:157], v[112:115]
	v_mfma_f32_16x16x32_bf16 v[104:107], v[138:141], v[154:157], v[104:107]
	v_mfma_f32_16x16x32_bf16 v[96:99], v[130:133], v[162:165], v[96:99]
	v_mfma_f32_16x16x32_bf16 v[88:91], v[138:141], v[162:165], v[88:91]
	v_mfma_f32_16x16x32_bf16 v[80:83], v[130:133], v[194:197], v[80:83]
	v_mfma_f32_16x16x32_bf16 v[72:75], v[138:141], v[194:197], v[72:75]
	v_mfma_f32_16x16x32_bf16 v[124:127], v[134:137], v[150:153], v[124:127]
	v_mfma_f32_16x16x32_bf16 v[120:123], v[142:145], v[150:153], v[120:123]
	v_mfma_f32_16x16x32_bf16 v[112:115], v[134:137], v[158:161], v[112:115]
	v_mfma_f32_16x16x32_bf16 v[104:107], v[142:145], v[158:161], v[104:107]
	v_mfma_f32_16x16x32_bf16 v[96:99], v[134:137], v[190:193], v[96:99]
	v_mfma_f32_16x16x32_bf16 v[88:91], v[142:145], v[190:193], v[88:91]
	v_mfma_f32_16x16x32_bf16 v[80:83], v[134:137], v[198:201], v[80:83]
	v_mfma_f32_16x16x32_bf16 v[72:75], v[142:145], v[198:201], v[72:75]
	s_barrier
	s_add_i32 s44, s46, s57
	v_add_u32_e32 v172, s78, v225
	v_lshl_add_u64 v[166:167], v[166:167], 0, s[88:89]
	s_mov_b32 m0, s44
	ds_read_b128 v[202:205], v172
	ds_read_b128 v[230:233], v172 offset:1024
	ds_read_b128 v[234:237], v172 offset:2048
	ds_read_b128 v[238:241], v172 offset:3072
	global_load_lds_dwordx4 v[166:167], off
	v_lshl_add_u64 v[166:167], v[206:207], 0, s[88:89]
	s_add_i32 m0, s44, 0x2000
	s_nop 0
	global_load_lds_dwordx4 v[166:167], off
	s_barrier
; #define PG8_STAGE(bufoff, gbase, voff) do { _Pragma("unroll") for (int _i = 0; _i < 2; ++_i) \
;         __builtin_amdgcn_global_load_lds((const unsigned*)((const char*)(gbase) + (voff)[_i]), (LAS unsigned*)(lds + (bufoff) + ldsw + _i * 8192), 16, 0, 0); } while (0)
; #define PG8_LDA(dst, b, h) do { _Pragma("unroll") for (int m = 0; m < 4; ++m) _Pragma("unroll") for (int k = 0; k < 2; ++k) dst[m][k] = *(const LAS bf16x8*)(lds + PG8_SA(b, h) + aoff + m * 2048 + k * 1024); } while (0)
; #define PG8_MMA(ai, bj, At, Bt) do { __builtin_amdgcn_s_setprio(1); _Pragma("unroll") for (int m = 0; m < 4; ++m) _Pragma("unroll") for (int n = 0; n < 2; ++n) _Pragma("unroll") for (int k = 0; k < 2; ++k) \
;         acc[ai][bj][m][n] = __builtin_amdgcn_mfma_f32_16x16x32_bf16(Bt[n][k], At[m][k], acc[ai][bj][m][n], 0, 0, 0); __builtin_amdgcn_s_setprio(0); } while (0)
; #define PG8_WAIT_V(n) asm volatile("s_waitcnt vmcnt(" #n ")" ::: "memory")
; #define PG8_WAIT_L(n) asm volatile("s_waitcnt lgkmcnt(" #n ")" ::: "memory")
; #define PG8_BAR __builtin_amdgcn_s_barrier()
; #define PG8_SCHED __builtin_amdgcn_sched_barrier(0)
; template <class Epi>
; __device__ __forceinline__ void gemm_phase(LAS unsigned char* lds, const Gemm g, const StaticOrder& S, const Epi& E) {
;     ...
;             PG8_BAR; PG8_WAIT_L(0); PG8_MMA(0, 1, At, B1); PG8_BAR;
;             PG8_LDA(At, 1, 1); PG8_STAGE(PG8_SA(1, 0), a3, voffA);
;             PG8_BAR; PG8_WAIT_L(0); PG8_MMA(1, 0, At, B0); PG8_BAR; PG8_SCHED;
;             PG8_STAGE(PG8_SB(1, 1), b3 + hstepB, voffB);
;             PG8_WAIT_V(6); PG8_BAR; PG8_MMA(1, 1, At, B1); PG8_BAR;
;         }
	s_waitcnt lgkmcnt(0)
	v_mfma_f32_16x16x32_bf16 v[116:119], v[202:205], v[146:149], v[116:119]
	v_mfma_f32_16x16x32_bf16 v[108:111], v[234:237], v[146:149], v[108:111]
	v_mfma_f32_16x16x32_bf16 v[100:103], v[202:205], v[154:157], v[100:103]
	v_mfma_f32_16x16x32_bf16 v[92:95], v[234:237], v[154:157], v[92:95]
	s_mov_b32 m0, s60
	v_lshl_add_u64 v[166:167], v[242:243], 0, s[88:89]
	v_mfma_f32_16x16x32_bf16 v[84:87], v[202:205], v[162:165], v[84:87]
	v_mfma_f32_16x16x32_bf16 v[76:79], v[234:237], v[162:165], v[76:79]
	v_mfma_f32_16x16x32_bf16 v[68:71], v[202:205], v[194:197], v[68:71]
	v_mfma_f32_16x16x32_bf16 v[64:67], v[234:237], v[194:197], v[64:67]
	v_mfma_f32_16x16x32_bf16 v[116:119], v[230:233], v[150:153], v[116:119]
	v_mfma_f32_16x16x32_bf16 v[108:111], v[238:241], v[150:153], v[108:111]
	v_mfma_f32_16x16x32_bf16 v[100:103], v[230:233], v[158:161], v[100:103]
	v_mfma_f32_16x16x32_bf16 v[92:95], v[238:241], v[158:161], v[92:95]
	v_mfma_f32_16x16x32_bf16 v[84:87], v[230:233], v[190:193], v[84:87]
	v_mfma_f32_16x16x32_bf16 v[76:79], v[238:241], v[190:193], v[76:79]
	v_mfma_f32_16x16x32_bf16 v[68:71], v[230:233], v[198:201], v[68:71]
	v_mfma_f32_16x16x32_bf16 v[64:67], v[238:241], v[198:201], v[64:67]
	s_barrier
	ds_read_b128 v[146:149], v228 offset:49152
	ds_read_b128 v[150:153], v228 offset:50176
	ds_read_b128 v[154:157], v228 offset:51200
	ds_read_b128 v[158:161], v228 offset:52224
	ds_read_b128 v[162:165], v228 offset:53248
	ds_read_b128 v[190:193], v228 offset:54272
	ds_read_b128 v[194:197], v228 offset:55296
	ds_read_b128 v[198:201], v228 offset:56320
	global_load_lds_dwordx4 v[166:167], off
	v_lshl_add_u64 v[166:167], v[244:245], 0, s[88:89]
	s_mov_b32 m0, s61
	s_nop 0
	global_load_lds_dwordx4 v[166:167], off
	s_waitcnt vmcnt(10)
	s_barrier
	s_waitcnt lgkmcnt(0)
	v_mfma_f32_16x16x32_bf16 v[60:63], v[130:133], v[146:149], v[60:63]
	v_mfma_f32_16x16x32_bf16 v[56:59], v[138:141], v[146:149], v[56:59]
	v_mfma_f32_16x16x32_bf16 v[52:55], v[130:133], v[154:157], v[52:55]
	v_mfma_f32_16x16x32_bf16 v[44:47], v[138:141], v[154:157], v[44:47]
	v_mfma_f32_16x16x32_bf16 v[36:39], v[130:133], v[162:165], v[36:39]
	v_mfma_f32_16x16x32_bf16 v[28:31], v[138:141], v[162:165], v[28:31]
	v_mfma_f32_16x16x32_bf16 v[20:23], v[130:133], v[194:197], v[20:23]
	v_mfma_f32_16x16x32_bf16 v[12:15], v[138:141], v[194:197], v[12:15]
	v_mfma_f32_16x16x32_bf16 v[60:63], v[134:137], v[150:153], v[60:63]
	v_mfma_f32_16x16x32_bf16 v[56:59], v[142:145], v[150:153], v[56:59]
	v_mfma_f32_16x16x32_bf16 v[52:55], v[134:137], v[158:161], v[52:55]
	v_mfma_f32_16x16x32_bf16 v[44:47], v[142:145], v[158:161], v[44:47]
	v_mfma_f32_16x16x32_bf16 v[36:39], v[134:137], v[190:193], v[36:39]
	v_mfma_f32_16x16x32_bf16 v[28:31], v[142:145], v[190:193], v[28:31]
	v_mfma_f32_16x16x32_bf16 v[20:23], v[134:137], v[198:201], v[20:23]
	v_mfma_f32_16x16x32_bf16 v[12:15], v[142:145], v[198:201], v[12:15]
	s_barrier
	s_add_i32 s44, s78, s57
	v_lshl_add_u64 v[130:131], v[246:247], 0, s[88:89]
	s_mov_b32 m0, s44
	s_nop 0
	global_load_lds_dwordx4 v[130:131], off
	v_lshl_add_u64 v[130:131], v[248:249], 0, s[88:89]
	s_add_i32 m0, s44, 0x2000
	s_nop 0
	global_load_lds_dwordx4 v[130:131], off
	v_add_u32_e32 v142, 0x10000, v225
	ds_read_b128 v[130:133], v142
	ds_read_b128 v[134:137], v142 offset:1024
	ds_read_b128 v[138:141], v142 offset:2048
	ds_read_b128 v[142:145], v142 offset:3072
	s_waitcnt vmcnt(6)
	s_barrier
	v_mfma_f32_16x16x32_bf16 v[48:51], v[202:205], v[146:149], v[48:51]
	v_mfma_f32_16x16x32_bf16 v[40:43], v[234:237], v[146:149], v[40:43]
	v_mfma_f32_16x16x32_bf16 v[32:35], v[202:205], v[154:157], v[32:35]
	v_mfma_f32_16x16x32_bf16 v[24:27], v[234:237], v[154:157], v[24:27]
	s_add_u32 s36, s36, 0x100
	s_addc_u32 s37, s37, 0
	s_add_u32 s69, s69, 0x100
	s_addc_u32 s70, s70, 0
	s_cmp_ge_u32 s35, s16
	s_mov_b32 s44, s35
	v_mfma_f32_16x16x32_bf16 v[16:19], v[202:205], v[162:165], v[16:19]
	v_mfma_f32_16x16x32_bf16 v[8:11], v[234:237], v[162:165], v[8:11]
	v_mfma_f32_16x16x32_bf16 v[4:7], v[202:205], v[194:197], v[4:7]
	v_mfma_f32_16x16x32_bf16 v[0:3], v[234:237], v[194:197], v[0:3]
	v_mfma_f32_16x16x32_bf16 v[48:51], v[230:233], v[150:153], v[48:51]
	v_mfma_f32_16x16x32_bf16 v[40:43], v[238:241], v[150:153], v[40:43]
	v_mfma_f32_16x16x32_bf16 v[32:35], v[230:233], v[158:161], v[32:35]
	v_mfma_f32_16x16x32_bf16 v[24:27], v[238:241], v[158:161], v[24:27]
	v_mfma_f32_16x16x32_bf16 v[16:19], v[230:233], v[190:193], v[16:19]
	v_mfma_f32_16x16x32_bf16 v[8:11], v[238:241], v[190:193], v[8:11]
	v_mfma_f32_16x16x32_bf16 v[4:7], v[230:233], v[198:201], v[4:7]
	v_mfma_f32_16x16x32_bf16 v[0:3], v[238:241], v[198:201], v[0:3]
	s_barrier
	s_cbranch_scc1 .LBB0_119
